# v114 + every P0 store write-through (silu table, rope table, weight copies, mod vectors) and no L2 write-back at the silu-table publish or at the barrier after P0
# speedup vs baseline: 1.0154x; 1.0026x over previous
; __device__ __forceinline__ u32x4 pack8(const float (&f)[8]) { u32x4 w; w.x = pk_bf16(f[0], f[1]); w.y = pk_bf16(f[2], f[3]); w.z = pk_bf16(f[4], f[5]); w.w = pk_bf16(f[6], f[7]); return w; }
; __device__ __forceinline__ float silu_f(float v) { return v * __builtin_amdgcn_rcpf(1.0f + __builtin_amdgcn_exp2f(-v * LOG2E_)); }
; __device__ __forceinline__ void p0_silu_table(const Args& a, int tid, int bid, int G) {
;     u32x4* tabs = (u32x4*)(a.ws + WS_SILU);
;     for (int e = bid * 512 + tid; e < 5 * 64 * 64; e += G * 512) {
;         const int ln = e & 63, ks = (e >> 6) & 63, rt = e >> 12;
;         const int row = 32 * rt + (ln & 31), k0 = 16 * ks + 8 * (ln >> 5);
;         u32x4 pw = {0u, 0u, 0u, 0u};
;         if (row < NMOD) {
;             const float* cp = row < NPB ? a.in[2] + (size_t)row * D : a.in[3] + (size_t)(row - NPB) * D;
;             const f32x4 c0 = *(const f32x4*)(cp + k0), c1 = *(const f32x4*)(cp + k0 + 4);
;             float cv[8] = {silu_f(c0.x), silu_f(c0.y), silu_f(c0.z), silu_f(c0.w), silu_f(c1.x), silu_f(c1.y), silu_f(c1.z), silu_f(c1.w)};
;             pw = pack8(cv);
;         }
;         tabs[e] = pw;
;     }
.LBB0_19:
	s_or_b64 exec, exec, s[12:13]
	v_add_u32_e32 v5, s6, v5
	v_cmp_lt_i32_e32 vcc, s14, v5
	global_store_dwordx4 v[6:7], v[0:3], off sc1
	s_or_b64 s[10:11], vcc, s[10:11]
	v_lshl_add_u64 v[6:7], v[6:7], 0, s[8:9]
	s_andn2_b64 exec, exec, s[10:11]
	s_cbranch_execz .LBB0_22

; __device__ __forceinline__ void p0_phase(const Args& a, LAS unsigned char* lds, int tid, int lane, int wave, int bid, int G) {
;     ...
;     const int nprod = (NENT + 511) / 512 < G ? (NENT + 511) / 512 : G;
;     p0_silu_table(a, tid, bid, G);
;     if (bid < nprod) {
;         asm volatile("s_waitcnt vmcnt(0)" ::: "memory");
;         __syncthreads();
;         if (tid == 0) { __builtin_amdgcn_fence(__ATOMIC_RELEASE, "agent"); asm volatile("s_waitcnt vmcnt(0)" ::: "memory");
;                         __hip_atomic_fetch_add(flag, 1u, __ATOMIC_RELAXED, __HIP_MEMORY_SCOPE_AGENT); }
.LBB0_22:
	s_or_b64 exec, exec, s[4:5]
	s_load_dwordx16 s[4:19], s[0:1], 0x40
	v_cmp_eq_u32_e32 vcc, 0, v114
	s_waitcnt lgkmcnt(0)
	v_writelane_b32 v253, s4, 20
	s_nop 1
	v_writelane_b32 v253, s5, 21
	v_writelane_b32 v253, s6, 22
	v_writelane_b32 v253, s7, 23
	v_writelane_b32 v253, s8, 24
	v_writelane_b32 v253, s9, 25
	v_writelane_b32 v253, s10, 26
	v_writelane_b32 v253, s11, 27
	v_writelane_b32 v253, s12, 28
	v_writelane_b32 v253, s13, 29
	v_writelane_b32 v253, s14, 30
	v_writelane_b32 v253, s15, 31
	v_writelane_b32 v253, s16, 32
	v_writelane_b32 v253, s17, 33
	v_writelane_b32 v253, s18, 34
	v_writelane_b32 v253, s19, 35
	s_add_u32 s10, s78, 0x1703a00
	s_addc_u32 s11, s79, 0
	s_min_i32 s23, s42, 40
	s_cmp_ge_i32 s71, s23
	s_cbranch_scc1 .LBB0_27
	s_waitcnt vmcnt(0)
	s_barrier
	s_and_saveexec_b64 s[0:1], vcc
	s_cbranch_execz .LBB0_26
	s_mov_b64 s[4:5], exec
	v_mbcnt_lo_u32_b32 v0, s4, 0
	s_waitcnt vmcnt(0)
	s_waitcnt vmcnt(0)
	v_mbcnt_hi_u32_b32 v0, s5, v0
	v_cmp_eq_u32_e32 vcc, 0, v0
	s_and_b64 s[6:7], exec, vcc
	s_mov_b64 exec, s[6:7]
	s_cbranch_execz .LBB0_26
	s_bcnt1_i32_b64 s3, s[4:5]
	v_mov_b32_e32 v0, 0
	v_mov_b32_e32 v1, s3
	global_atomic_add v0, v1, s[10:11]

; __device__ __forceinline__ void p0_rope(const Args& a, int tid, int bid, int G) {
;     float* tab = (float*)(a.ws + WS_ROPE);
;     for (int e = bid * 512 + tid; e < (LP + LS) * 8; e += G * 512) {
;         const int p = e >> 3, j = e & 7;
;         const float pos = (float)(p < LP ? p : 8192 + (p - LP));
;         const float inv = (float)exp(-(double)j * 1.640295422175541);
;         const float angf = pos * inv;
;         const double ang = (double)angf;
;         const double twopi = 6.283185307179586476925;
;         const double kk = __builtin_rint(ang / twopi);
;         const float red = (float)(ang - kk * twopi);
;         tab[p * 16 + j] = cosf(red); tab[p * 16 + 8 + j] = sinf(red);
;     }
.LBB0_29:
	s_or_b64 exec, exec, s[0:1]
	v_mul_f32_e32 v0, v17, v17
	v_fmamk_f32 v14, v0, 0xb94c1982, v7
	v_fmaak_f32 v14, v0, v14, 0xbe2aaa9d
	v_mul_f32_e32 v14, v0, v14
	v_fmac_f32_e32 v17, v17, v14
	v_fmamk_f32 v14, v0, 0x37d75334, v8
	v_fmaak_f32 v14, v0, v14, 0x3d2aabf7
	v_fmaak_f32 v14, v0, v14, 0xbf000004
	v_fma_f32 v0, v0, v14, 1.0
	v_and_b32_e32 v14, 1, v16
	v_cmp_eq_u32_e64 s[0:1], 0, v14
	v_lshlrev_b32_e32 v14, 30, v16
	v_and_b32_e32 v14, 0x80000000, v14
	v_xor_b32_e32 v12, v13, v12
	v_cndmask_b32_e64 v0, v0, v17, s[0:1]
	v_xor_b32_e32 v12, v12, v14
	v_xor_b32_e32 v0, v12, v0
	v_add_u32_e32 v4, s3, v4
	v_cndmask_b32_e32 v0, v11, v0, vcc
	v_cmp_lt_i32_e32 vcc, s39, v4
	s_or_b64 s[14:15], vcc, s[14:15]
	global_store_dword v[2:3], v0, off offset:32 sc1
	s_andn2_b64 exec, exec, s[14:15]
	s_cbranch_execz .LBB0_38

; __device__ __forceinline__ void p0_rope(const Args& a, int tid, int bid, int G) {
;     float* tab = (float*)(a.ws + WS_ROPE);
;     for (int e = bid * 512 + tid; e < (LP + LS) * 8; e += G * 512) {
;         const int p = e >> 3, j = e & 7;
;         const float pos = (float)(p < LP ? p : 8192 + (p - LP));
;         const float inv = (float)exp(-(double)j * 1.640295422175541);
;         const float angf = pos * inv;
;         const double ang = (double)angf;
;         const double twopi = 6.283185307179586476925;
;         const double kk = __builtin_rint(ang / twopi);
;         const float red = (float)(ang - kk * twopi);
;         tab[p * 16 + j] = cosf(red); tab[p * 16 + 8 + j] = sinf(red);
;     }
.LBB0_32:
	s_or_saveexec_b64 s[0:1], s[20:21]
	v_mul_f32_e64 v0, |v12|, s35
	v_rndne_f32_e32 v0, v0
	s_xor_b64 exec, exec, s[0:1]
	v_cvt_i32_f32_e32 v3, v0
	v_fma_f32 v16, v0, s36, |v12|
	v_fmac_f32_e32 v16, 0xb3a22168, v0
	v_fmac_f32_e32 v16, 0xa7c234c4, v0
	s_or_b64 exec, exec, s[0:1]
	v_mul_f32_e32 v17, v16, v16
	v_fmamk_f32 v18, v17, 0xb94c1982, v7
	v_fmaak_f32 v18, v17, v18, 0xbe2aaa9d
	v_mul_f32_e32 v18, v17, v18
	v_fmac_f32_e32 v16, v16, v18
	v_fmamk_f32 v18, v17, 0x37d75334, v8
	v_fmaak_f32 v18, v17, v18, 0x3d2aabf7
	v_fmaak_f32 v18, v17, v18, 0xbf000004
	v_fma_f32 v17, v17, v18, 1.0
	v_and_b32_e32 v18, 1, v3
	v_cmp_eq_u32_e32 vcc, 0, v18
	v_lshlrev_b32_e32 v3, 30, v3
	v_lshl_or_b32 v2, v2, 4, v5
	v_cndmask_b32_e64 v16, -v16, v17, vcc
	v_bitop3_b32 v3, v3, v16, s37 bitop3:0x6c
	v_cmp_class_f32_e64 vcc, v12, s38
	s_nop 1
	v_cndmask_b32_e32 v16, v11, v3, vcc
	v_ashrrev_i32_e32 v3, 31, v2
	v_lshl_add_u64 v[2:3], v[2:3], 2, s[48:49]
	global_store_dword v[2:3], v16, off sc1
	s_and_saveexec_b64 s[0:1], s[8:9]
	s_xor_b64 s[20:21], exec, s[0:1]
	s_cbranch_execz .LBB0_36
	v_cmp_lt_u32_e64 s[0:1], 63, v15
	v_mad_u64_u32 v[16:17], s[8:9], v14, s26, 0
	s_nop 0
	v_cndmask_b32_e64 v0, 0, v9, s[0:1]
	v_add_u32_e32 v0, v0, v15
	v_cmp_lt_u32_e64 s[4:5], 31, v0
	s_nop 1
	v_cndmask_b32_e64 v15, 0, v10, s[4:5]
	v_add_u32_e32 v0, v15, v0
	v_cmp_lt_u32_e64 s[6:7], 31, v0
	s_nop 1
	v_cndmask_b32_e64 v15, 0, v10, s[6:7]
	v_add_u32_e32 v28, v15, v0
	v_mov_b32_e32 v0, v17
	v_mad_u64_u32 v[18:19], s[8:9], v14, s27, v[0:1]
	v_mov_b32_e32 v0, v19
	v_mad_u64_u32 v[20:21], s[8:9], v14, s28, v[0:1]
	v_mov_b32_e32 v0, v21
	v_mad_u64_u32 v[22:23], s[8:9], v14, s29, v[0:1]
	v_mov_b32_e32 v0, v23
	v_mad_u64_u32 v[24:25], s[8:9], v14, s30, v[0:1]
	v_mov_b32_e32 v0, v25
	v_mad_u64_u32 v[26:27], s[8:9], v14, s31, v[0:1]
	v_mov_b32_e32 v0, v27
	v_mad_u64_u32 v[14:15], s[8:9], v14, s33, v[0:1]
	v_cndmask_b32_e64 v17, v26, v22, s[0:1]
	v_cndmask_b32_e64 v0, v14, v24, s[0:1]
	v_cndmask_b32_e64 v15, v15, v26, s[0:1]
	v_cndmask_b32_e64 v14, v0, v17, s[4:5]
	v_cndmask_b32_e64 v0, v15, v0, s[4:5]
	v_cndmask_b32_e64 v15, v24, v20, s[0:1]
	v_cndmask_b32_e64 v17, v17, v15, s[4:5]
	v_cndmask_b32_e64 v18, v22, v18, s[0:1]
	v_cndmask_b32_e64 v0, v0, v14, s[6:7]
	v_cndmask_b32_e64 v14, v14, v17, s[6:7]
	v_sub_u32_e32 v19, 32, v28
	v_cndmask_b32_e64 v15, v15, v18, s[4:5]
	v_alignbit_b32 v21, v0, v14, v19
	v_cmp_eq_u32_e64 s[8:9], 0, v28
	v_cndmask_b32_e64 v17, v17, v15, s[6:7]
	v_cndmask_b32_e64 v16, v20, v16, s[0:1]
	v_cndmask_b32_e64 v0, v21, v0, s[8:9]
	v_alignbit_b32 v21, v14, v17, v19
	v_cndmask_b32_e64 v14, v21, v14, s[8:9]
	v_bfe_u32 v23, v0, 29, 1
	v_cndmask_b32_e64 v16, v18, v16, s[4:5]
	v_alignbit_b32 v21, v0, v14, 30
	v_sub_u32_e32 v24, 0, v23
	v_cndmask_b32_e64 v15, v15, v16, s[6:7]
	v_xor_b32_e32 v21, v21, v24
	v_alignbit_b32 v16, v17, v15, v19
	v_cndmask_b32_e64 v16, v16, v17, s[8:9]
	v_ffbh_u32_e32 v17, v21
	v_alignbit_b32 v14, v14, v16, 30
	v_min_u32_e32 v17, 32, v17
	v_alignbit_b32 v15, v16, v15, 30
	v_xor_b32_e32 v14, v14, v24
	v_sub_u32_e32 v18, 31, v17
	v_xor_b32_e32 v15, v15, v24
	v_alignbit_b32 v19, v21, v14, v18
	v_alignbit_b32 v14, v14, v15, v18
	v_alignbit_b32 v15, v19, v14, 9
	v_ffbh_u32_e32 v16, v15
	v_min_u32_e32 v16, 32, v16
	v_lshrrev_b32_e32 v22, 29, v0
	v_not_b32_e32 v18, v16
	v_alignbit_b32 v14, v15, v14, v18
	v_lshlrev_b32_e32 v15, 31, v22
	v_or_b32_e32 v18, 0x33000000, v15
	v_add_lshl_u32 v16, v16, v17, 23
	v_lshrrev_b32_e32 v14, 9, v14
	v_sub_u32_e32 v16, v18, v16
	v_or_b32_e32 v15, 0.5, v15
	v_lshlrev_b32_e32 v17, 23, v17
	v_or_b32_e32 v14, v16, v14
	v_lshrrev_b32_e32 v16, 9, v19
	v_sub_u32_e32 v15, v15, v17
	v_or_b32_e32 v15, v16, v15
	v_mul_f32_e32 v16, 0x3fc90fda, v15
	v_fma_f32 v17, v15, s34, -v16
	v_fmac_f32_e32 v17, 0x33a22168, v15
	v_fmac_f32_e32 v17, 0x3fc90fda, v14
	v_lshrrev_b32_e32 v0, 30, v0
	v_add_f32_e32 v17, v16, v17
	v_add_u32_e32 v16, v23, v0

; #define LAS __attribute__((address_space(3)))
; template <bool REMAP>
; __device__ __forceinline__ void p0_transpose_item(const float* W, int K, int N, bf16_t* WT, LAS float* scr, int item, int lane) {
;     const int nblk = N / 32, kb = item / nblk, nb = item % nblk, k0 = 64 * kb, n0 = 32 * nb;
;     const int r0 = REMAP ? win_row_of_col(n0) : n0;
; #pragma unroll
;     for (int i = 0; i < 32; ++i) { const int kk = 2 * i + (lane >> 5); scr[kk * 33 + (lane & 31)] = __builtin_nontemporal_load(W + (size_t)(k0 + kk) * N + n0 + (lane & 31)); }
;     asm volatile("s_waitcnt lgkmcnt(0)" ::: "memory");
.LBB0_40:
	s_lshl_b32 s4, s7, 6
	s_ashr_i32 s7, s6, 31
	v_lshl_add_u64 v[10:11], s[6:7], 2, v[8:9]
	v_or_b32_e32 v0, s4, v12
	v_mad_i64_i32 v[58:59], s[6:7], v0, s24, v[10:11]
	v_or_b32_e32 v0, s4, v13
	v_mad_i64_i32 v[60:61], s[6:7], v0, s24, v[10:11]
	v_or_b32_e32 v0, s4, v14
	v_mad_i64_i32 v[62:63], s[6:7], v0, s24, v[10:11]
	v_or_b32_e32 v0, s4, v15
	v_mad_i64_i32 v[64:65], s[6:7], v0, s24, v[10:11]
	v_or_b32_e32 v0, s4, v16
	v_mad_i64_i32 v[66:67], s[6:7], v0, s24, v[10:11]
	v_or_b32_e32 v0, s4, v17
	v_mad_i64_i32 v[68:69], s[6:7], v0, s24, v[10:11]
	v_or_b32_e32 v0, s4, v18
	v_mad_i64_i32 v[70:71], s[6:7], v0, s24, v[10:11]
	v_or_b32_e32 v0, s4, v19
	v_mad_i64_i32 v[72:73], s[6:7], v0, s24, v[10:11]
	global_load_dword v0, v[58:59], off nt
	global_load_dword v74, v[60:61], off nt
	global_load_dword v75, v[62:63], off nt
	global_load_dword v76, v[64:65], off nt
	global_load_dword v77, v[66:67], off nt
	global_load_dword v78, v[68:69], off nt
	global_load_dword v79, v[70:71], off nt
	global_load_dword v80, v[72:73], off nt
	v_or_b32_e32 v58, s4, v20
	v_or_b32_e32 v60, s4, v21
	v_or_b32_e32 v62, s4, v22
	v_or_b32_e32 v64, s4, v23
	v_or_b32_e32 v66, s4, v24
	v_or_b32_e32 v68, s4, v25
	v_or_b32_e32 v70, s4, v26
	v_or_b32_e32 v72, s4, v27
	v_mad_i64_i32 v[58:59], s[6:7], v58, s24, v[10:11]
	v_mad_i64_i32 v[60:61], s[6:7], v60, s24, v[10:11]
	v_mad_i64_i32 v[62:63], s[6:7], v62, s24, v[10:11]
	v_mad_i64_i32 v[64:65], s[6:7], v64, s24, v[10:11]
	v_mad_i64_i32 v[66:67], s[6:7], v66, s24, v[10:11]
	v_mad_i64_i32 v[68:69], s[6:7], v68, s24, v[10:11]
	v_mad_i64_i32 v[70:71], s[6:7], v70, s24, v[10:11]
	v_mad_i64_i32 v[72:73], s[6:7], v72, s24, v[10:11]
	global_load_dword v81, v[58:59], off nt
	global_load_dword v82, v[60:61], off nt
	global_load_dword v83, v[62:63], off nt
	global_load_dword v84, v[64:65], off nt
	global_load_dword v85, v[66:67], off nt
	global_load_dword v86, v[68:69], off nt
	global_load_dword v87, v[70:71], off nt
	global_load_dword v88, v[72:73], off nt
	v_or_b32_e32 v58, s4, v28
	v_or_b32_e32 v60, s4, v29
	v_or_b32_e32 v62, s4, v30
	v_or_b32_e32 v64, s4, v31
	v_or_b32_e32 v66, s4, v32
	v_or_b32_e32 v68, s4, v33
	v_or_b32_e32 v70, s4, v34
	v_or_b32_e32 v72, s4, v35
	v_mad_i64_i32 v[58:59], s[6:7], v58, s24, v[10:11]
	v_mad_i64_i32 v[60:61], s[6:7], v60, s24, v[10:11]
	v_mad_i64_i32 v[62:63], s[6:7], v62, s24, v[10:11]
	v_mad_i64_i32 v[64:65], s[6:7], v64, s24, v[10:11]
	v_mad_i64_i32 v[66:67], s[6:7], v66, s24, v[10:11]
	v_mad_i64_i32 v[68:69], s[6:7], v68, s24, v[10:11]
	v_mad_i64_i32 v[70:71], s[6:7], v70, s24, v[10:11]
	v_mad_i64_i32 v[72:73], s[6:7], v72, s24, v[10:11]
	global_load_dword v89, v[58:59], off nt
	global_load_dword v90, v[60:61], off nt
	global_load_dword v91, v[62:63], off nt
	global_load_dword v92, v[64:65], off nt
	global_load_dword v93, v[66:67], off nt
	global_load_dword v94, v[68:69], off nt
	global_load_dword v95, v[70:71], off nt
	s_nop 0
	global_load_dword v72, v[72:73], off nt
	v_or_b32_e32 v58, s4, v36
	v_or_b32_e32 v60, s4, v37
	v_or_b32_e32 v62, s4, v38
	v_or_b32_e32 v64, s4, v39
	v_or_b32_e32 v66, s4, v40
	v_or_b32_e32 v68, s4, v41
	v_or_b32_e32 v70, s4, v42
	v_or_b32_e32 v73, s4, v43
	v_mad_i64_i32 v[58:59], s[6:7], v58, s24, v[10:11]
	v_mad_i64_i32 v[60:61], s[6:7], v60, s24, v[10:11]
	v_mad_i64_i32 v[62:63], s[6:7], v62, s24, v[10:11]
	v_mad_i64_i32 v[64:65], s[6:7], v64, s24, v[10:11]
	v_mad_i64_i32 v[66:67], s[6:7], v66, s24, v[10:11]
	v_mad_i64_i32 v[68:69], s[6:7], v68, s24, v[10:11]
	v_mad_i64_i32 v[70:71], s[6:7], v70, s24, v[10:11]
	v_mad_i64_i32 v[10:11], s[6:7], v73, s24, v[10:11]
	global_load_dword v58, v[58:59], off nt
	s_nop 0
	global_load_dword v59, v[60:61], off nt
	s_nop 0
	global_load_dword v60, v[62:63], off nt
	global_load_dword v61, v[64:65], off nt
	s_nop 0
	global_load_dword v62, v[66:67], off nt
	global_load_dword v63, v[68:69], off nt
	global_load_dword v64, v[70:71], off nt
	s_nop 0
	global_load_dword v10, v[10:11], off nt
	s_waitcnt vmcnt(30)
	ds_write2_b32 v49, v0, v74 offset1:66
	s_waitcnt vmcnt(28)
	ds_write2_b32 v49, v75, v76 offset0:132 offset1:198
	s_waitcnt vmcnt(26)
	ds_write2_b32 v52, v77, v78 offset0:8 offset1:74
	s_waitcnt vmcnt(24)
	ds_write2_b32 v50, v79, v80 offset1:66
	s_waitcnt vmcnt(22)
	ds_write2_b32 v50, v81, v82 offset0:132 offset1:198
	s_waitcnt vmcnt(20)
	ds_write2_b32 v53, v83, v84 offset0:8 offset1:74
	s_waitcnt vmcnt(18)
	ds_write2_b32 v51, v85, v86 offset1:66
	s_waitcnt vmcnt(16)
	ds_write2_b32 v51, v87, v88 offset0:132 offset1:198
	s_waitcnt vmcnt(14)
	ds_write2_b32 v54, v89, v90 offset0:8 offset1:74
	s_waitcnt vmcnt(12)
	ds_write2_b32 v54, v91, v92 offset0:140 offset1:206
	s_waitcnt vmcnt(10)
	ds_write2_b32 v55, v93, v94 offset0:16 offset1:82
	s_waitcnt vmcnt(8)
	ds_write2_b32 v55, v95, v72 offset0:148 offset1:214
	s_waitcnt vmcnt(6)
; #define LAS __attribute__((address_space(3)))
; __device__ __forceinline__ unsigned pk2(float lo, float hi) { return f2bf_rne(lo) | (f2bf_rne(hi) << 16); }
; template <bool REMAP>
; __device__ __forceinline__ void p0_transpose_item(const float* W, int K, int N, bf16_t* WT, LAS float* scr, int item, int lane) {
;     ...
;     const int c = lane & 7;
; #pragma unroll
;     for (int j = 0; j < 4; ++j) { const int n = (lane >> 3) + 8 * j; const LAS float* s = scr + (8 * c) * 33 + n;
;         u32x4 o; o.x = pk2(s[0 * 33], s[1 * 33]); o.y = pk2(s[2 * 33], s[3 * 33]); o.z = pk2(s[4 * 33], s[5 * 33]); o.w = pk2(s[6 * 33], s[7 * 33]);
;         *(u32x4*)(WT + (size_t)(r0 + n) * K + k0 + 8 * c) = o; }
;     asm volatile("s_waitcnt lgkmcnt(0)" ::: "memory");
	ds_write2_b32 v56, v58, v59 offset0:24 offset1:90
	s_waitcnt vmcnt(4)
	ds_write2_b32 v56, v60, v61 offset0:156 offset1:222
	s_waitcnt vmcnt(2)
	ds_write2_b32 v57, v62, v63 offset0:32 offset1:98
	s_waitcnt vmcnt(0)
	ds_write2_b32 v57, v64, v10 offset0:164 offset1:230
	s_waitcnt lgkmcnt(0)
	ds_read2_b32 v[10:11], v45 offset1:8
	ds_read2_b32 v[62:63], v45 offset0:33 offset1:41
	ds_read2_b32 v[64:65], v45 offset0:66 offset1:74
	ds_read2_b32 v[66:67], v45 offset0:99 offset1:107
	ds_read2_b32 v[68:69], v45 offset0:132 offset1:140
	ds_read2_b32 v[70:71], v45 offset0:165 offset1:173
	s_waitcnt lgkmcnt(5)
	v_bfe_u32 v0, v10, 16, 1
	s_waitcnt lgkmcnt(3)
	v_bfe_u32 v58, v64, 16, 1
	v_add3_u32 v0, v10, v0, s20
	v_bfe_u32 v10, v62, 16, 1
	v_add3_u32 v58, v64, v58, s20
	ds_read2_b32 v[72:73], v45 offset0:198 offset1:206
	v_lshrrev_b32_e32 v0, 16, v0
	v_add3_u32 v10, v62, v10, s20
	v_lshrrev_b32_e32 v59, 16, v58
	s_waitcnt lgkmcnt(3)
	v_bfe_u32 v58, v66, 16, 1
	ds_read2_b32 v[74:75], v45 offset0:231 offset1:239
	v_add3_u32 v60, v66, v58, s20
	v_and_or_b32 v58, v10, s21, v0
	s_waitcnt lgkmcnt(3)
	v_bfe_u32 v0, v68, 16, 1
	v_add3_u32 v0, v68, v0, s20
	s_waitcnt lgkmcnt(2)
	v_bfe_u32 v10, v70, 16, 1
	v_lshrrev_b32_e32 v0, 16, v0
	v_add3_u32 v10, v70, v10, s20
	v_and_or_b32 v59, v60, s21, v59
	v_and_or_b32 v60, v10, s21, v0
	s_waitcnt lgkmcnt(1)
	v_bfe_u32 v0, v72, 16, 1
	v_add3_u32 v0, v72, v0, s20
	s_waitcnt lgkmcnt(0)
	v_bfe_u32 v10, v74, 16, 1
	v_lshrrev_b32_e32 v0, 16, v0
	v_add3_u32 v10, v74, v10, s20
	s_ashr_i32 s5, s4, 31
	v_and_or_b32 v61, v10, s21, v0
	v_add_lshl_u32 v0, s0, v44, 11
	v_lshl_add_u64 v[76:77], s[4:5], 1, v[2:3]
	v_lshl_add_u64 v[78:79], v[76:77], 0, v[0:1]
	v_bfe_u32 v0, v11, 16, 1
	v_add3_u32 v0, v11, v0, s20
	v_bfe_u32 v10, v63, 16, 1
	global_store_dwordx4 v[78:79], v[58:61], off sc1
	v_add3_u32 v10, v63, v10, s20
	v_lshrrev_b32_e32 v0, 16, v0
	v_bfe_u32 v58, v67, 16, 1
	v_add3_u32 v59, v67, v58, s20
	v_and_or_b32 v58, v10, s21, v0
	v_bfe_u32 v0, v69, 16, 1
	v_add3_u32 v0, v69, v0, s20
	v_bfe_u32 v10, v71, 16, 1
	v_add3_u32 v10, v71, v10, s20
	v_lshrrev_b32_e32 v0, 16, v0
	v_and_or_b32 v60, v10, s21, v0
	v_bfe_u32 v0, v73, 16, 1
	v_bfe_u32 v11, v65, 16, 1
	v_add3_u32 v0, v73, v0, s20
	v_bfe_u32 v10, v75, 16, 1
	v_add3_u32 v11, v65, v11, s20
	v_add3_u32 v10, v75, v10, s20
	v_lshrrev_b32_e32 v0, 16, v0
	v_lshrrev_b32_e32 v11, 16, v11
	v_and_or_b32 v61, v10, s21, v0
	v_add_lshl_u32 v0, s0, v46, 11
	v_and_or_b32 v59, v59, s21, v11
	ds_read2_b32 v[10:11], v45 offset0:16 offset1:24
	v_lshl_add_u64 v[62:63], v[76:77], 0, v[0:1]
	ds_read2_b32 v[64:65], v45 offset0:82 offset1:90
	global_store_dwordx4 v[62:63], v[58:61], off sc1
	ds_read2_b32 v[62:63], v45 offset0:49 offset1:57
	ds_read2_b32 v[66:67], v45 offset0:115 offset1:123
	ds_read2_b32 v[68:69], v45 offset0:148 offset1:156
	ds_read2_b32 v[70:71], v45 offset0:181 offset1:189
	s_waitcnt lgkmcnt(5)
	v_bfe_u32 v0, v10, 16, 1
	s_waitcnt lgkmcnt(4)
	v_bfe_u32 v58, v64, 16, 1
	v_add3_u32 v0, v10, v0, s20
	s_waitcnt lgkmcnt(3)
	v_bfe_u32 v10, v62, 16, 1
	v_add3_u32 v58, v64, v58, s20
	ds_read2_b32 v[72:73], v45 offset0:214 offset1:222
	v_lshrrev_b32_e32 v0, 16, v0
	v_add3_u32 v10, v62, v10, s20
	v_lshrrev_b32_e32 v59, 16, v58
	s_waitcnt lgkmcnt(3)
	v_bfe_u32 v58, v66, 16, 1
	ds_read2_b32 v[74:75], v45 offset0:247 offset1:255
	v_add3_u32 v60, v66, v58, s20
	v_and_or_b32 v58, v10, s21, v0
	s_waitcnt lgkmcnt(3)
	v_bfe_u32 v0, v68, 16, 1
	v_add3_u32 v0, v68, v0, s20
	s_waitcnt lgkmcnt(2)
	v_bfe_u32 v10, v70, 16, 1
	v_lshrrev_b32_e32 v0, 16, v0
	v_add3_u32 v10, v70, v10, s20
	v_and_or_b32 v59, v60, s21, v59
	v_and_or_b32 v60, v10, s21, v0
	s_waitcnt lgkmcnt(1)
	v_bfe_u32 v0, v72, 16, 1
	v_add3_u32 v0, v72, v0, s20
	s_waitcnt lgkmcnt(0)
	v_bfe_u32 v10, v74, 16, 1
	v_lshrrev_b32_e32 v0, 16, v0
	v_add3_u32 v10, v74, v10, s20
	v_and_or_b32 v61, v10, s21, v0
	v_add_lshl_u32 v0, s0, v47, 11
	v_lshl_add_u64 v[78:79], v[76:77], 0, v[0:1]
	v_bfe_u32 v0, v11, 16, 1
	v_add3_u32 v0, v11, v0, s20
	v_bfe_u32 v10, v63, 16, 1
	global_store_dwordx4 v[78:79], v[58:61], off sc1
	v_add3_u32 v10, v63, v10, s20
	v_lshrrev_b32_e32 v0, 16, v0
	v_bfe_u32 v58, v67, 16, 1
	v_add3_u32 v59, v67, v58, s20
	v_and_or_b32 v58, v10, s21, v0
	v_bfe_u32 v0, v69, 16, 1
	v_add3_u32 v0, v69, v0, s20
	v_bfe_u32 v10, v71, 16, 1
	v_add3_u32 v10, v71, v10, s20
	v_lshrrev_b32_e32 v0, 16, v0
	v_and_or_b32 v60, v10, s21, v0
	v_bfe_u32 v0, v73, 16, 1
	v_bfe_u32 v11, v65, 16, 1
	v_add3_u32 v0, v73, v0, s20
	v_bfe_u32 v10, v75, 16, 1
	v_add3_u32 v11, v65, v11, s20
	v_add3_u32 v10, v75, v10, s20
	v_lshrrev_b32_e32 v0, 16, v0
	v_lshrrev_b32_e32 v11, 16, v11
	v_and_or_b32 v61, v10, s21, v0
	v_add_lshl_u32 v0, s0, v48, 11
	v_and_or_b32 v59, v59, s21, v11
	v_lshl_add_u64 v[10:11], v[76:77], 0, v[0:1]
	global_store_dwordx4 v[10:11], v[58:61], off sc1
	s_waitcnt lgkmcnt(0)

; #define LAS __attribute__((address_space(3)))
; template <bool REMAP>
; __device__ __forceinline__ void p0_transpose_item(const float* W, int K, int N, bf16_t* WT, LAS float* scr, int item, int lane) {
;     const int nblk = N / 32, kb = item / nblk, nb = item % nblk, k0 = 64 * kb, n0 = 32 * nb;
;     const int r0 = REMAP ? win_row_of_col(n0) : n0;
; #pragma unroll
;     for (int i = 0; i < 32; ++i) { const int kk = 2 * i + (lane >> 5); scr[kk * 33 + (lane & 31)] = __builtin_nontemporal_load(W + (size_t)(k0 + kk) * N + n0 + (lane & 31)); }
;     asm volatile("s_waitcnt lgkmcnt(0)" ::: "memory");
; __device__ __forceinline__ void transposes_layer(const Args& a, int l, LAS unsigned char* lds, int lane, int wave, int vrot, int nvb) {
;     ...
;     for (int it = vrot * 8 + wave; it < I_IN + I_OUT; it += nvb * 8) {
;         if (it < I_IN) p0_transpose_item<true>(a.in[10] + (size_t)l * D * PO, D, PO, WinT, scr, it, lane);
;         else p0_transpose_item<false>(a.in[15] + (size_t)l * D * D, D, D, WoutT, scr, it - I_IN, lane);
.LBB0_42:
	s_cmpk_gt_i32 s14, 0x67f
	s_mov_b64 s[4:5], -1
	s_cbranch_scc0 .LBB0_44
	s_add_i32 s0, s16, 0xffff3000
	s_and_b32 s5, s18, 0x3c0
	s_and_b32 s4, s0, 0x3e0
	s_lshl_b32 s0, s4, 2
	v_or_b32_e32 v0, s5, v12
	v_lshl_add_u64 v[10:11], v[6:7], 0, s[0:1]
	v_lshlrev_b32_e32 v0, 12, v0
	v_lshl_add_u64 v[58:59], v[10:11], 0, v[0:1]
	v_or_b32_e32 v0, s5, v13
	v_lshlrev_b32_e32 v0, 12, v0
	v_lshl_add_u64 v[60:61], v[10:11], 0, v[0:1]
	v_or_b32_e32 v0, s5, v14
	v_lshlrev_b32_e32 v0, 12, v0
	v_lshl_add_u64 v[62:63], v[10:11], 0, v[0:1]
	v_or_b32_e32 v0, s5, v15
	v_lshlrev_b32_e32 v0, 12, v0
	v_lshl_add_u64 v[64:65], v[10:11], 0, v[0:1]
	v_or_b32_e32 v0, s5, v16
	v_lshlrev_b32_e32 v0, 12, v0
	v_lshl_add_u64 v[66:67], v[10:11], 0, v[0:1]
	v_or_b32_e32 v0, s5, v17
	v_lshlrev_b32_e32 v0, 12, v0
	v_lshl_add_u64 v[68:69], v[10:11], 0, v[0:1]
	v_or_b32_e32 v0, s5, v18
	v_lshlrev_b32_e32 v0, 12, v0
	v_lshl_add_u64 v[70:71], v[10:11], 0, v[0:1]
	v_or_b32_e32 v0, s5, v19
	v_lshlrev_b32_e32 v0, 12, v0
	v_lshl_add_u64 v[72:73], v[10:11], 0, v[0:1]
	v_or_b32_e32 v0, s5, v20
	global_load_dword v74, v[58:59], off nt
	global_load_dword v75, v[60:61], off nt
	global_load_dword v76, v[62:63], off nt
	global_load_dword v77, v[64:65], off nt
	global_load_dword v78, v[66:67], off nt
	global_load_dword v79, v[68:69], off nt
	global_load_dword v80, v[70:71], off nt
	global_load_dword v81, v[72:73], off nt
	v_or_b32_e32 v60, s5, v21
	v_lshlrev_b32_e32 v0, 12, v0
	v_or_b32_e32 v62, s5, v22
	v_lshl_add_u64 v[58:59], v[10:11], 0, v[0:1]
	v_lshlrev_b32_e32 v0, 12, v60
	v_or_b32_e32 v64, s5, v23
	v_lshl_add_u64 v[60:61], v[10:11], 0, v[0:1]
	v_lshlrev_b32_e32 v0, 12, v62
	v_or_b32_e32 v66, s5, v24
	v_lshl_add_u64 v[62:63], v[10:11], 0, v[0:1]
	v_lshlrev_b32_e32 v0, 12, v64
	v_or_b32_e32 v68, s5, v25
	v_lshl_add_u64 v[64:65], v[10:11], 0, v[0:1]
	v_lshlrev_b32_e32 v0, 12, v66
	v_or_b32_e32 v70, s5, v26
	v_lshl_add_u64 v[66:67], v[10:11], 0, v[0:1]
	v_lshlrev_b32_e32 v0, 12, v68
	v_or_b32_e32 v72, s5, v27
	v_lshl_add_u64 v[68:69], v[10:11], 0, v[0:1]
	v_lshlrev_b32_e32 v0, 12, v70
	v_or_b32_e32 v82, s5, v28
	v_lshl_add_u64 v[70:71], v[10:11], 0, v[0:1]
	v_lshlrev_b32_e32 v0, 12, v72
	v_or_b32_e32 v83, s5, v29
	v_lshl_add_u64 v[72:73], v[10:11], 0, v[0:1]
	v_lshlrev_b32_e32 v0, 12, v82
	v_or_b32_e32 v84, s5, v30
	global_load_dword v85, v[58:59], off nt
	global_load_dword v86, v[60:61], off nt
	global_load_dword v87, v[62:63], off nt
	global_load_dword v88, v[64:65], off nt
	global_load_dword v89, v[66:67], off nt
	global_load_dword v90, v[68:69], off nt
	global_load_dword v91, v[70:71], off nt
	global_load_dword v92, v[72:73], off nt
	v_lshl_add_u64 v[58:59], v[10:11], 0, v[0:1]
	v_lshlrev_b32_e32 v0, 12, v83
	v_or_b32_e32 v82, s5, v31
	v_lshl_add_u64 v[60:61], v[10:11], 0, v[0:1]
	v_lshlrev_b32_e32 v0, 12, v84
	v_or_b32_e32 v66, s5, v32
	v_lshl_add_u64 v[62:63], v[10:11], 0, v[0:1]
	v_lshlrev_b32_e32 v0, 12, v82
	v_or_b32_e32 v68, s5, v33
	v_lshl_add_u64 v[64:65], v[10:11], 0, v[0:1]
	v_lshlrev_b32_e32 v0, 12, v66
	v_lshl_add_u64 v[66:67], v[10:11], 0, v[0:1]
	v_lshlrev_b32_e32 v0, 12, v68
	v_lshl_add_u64 v[68:69], v[10:11], 0, v[0:1]
	v_or_b32_e32 v0, s5, v34
	v_lshlrev_b32_e32 v0, 12, v0
	v_lshl_add_u64 v[70:71], v[10:11], 0, v[0:1]
	v_or_b32_e32 v0, s5, v35
	v_lshlrev_b32_e32 v0, 12, v0
	v_lshl_add_u64 v[72:73], v[10:11], 0, v[0:1]
	v_or_b32_e32 v0, s5, v36
	v_lshlrev_b32_e32 v0, 12, v0
	global_load_dword v82, v[58:59], off nt
	global_load_dword v83, v[60:61], off nt
	global_load_dword v84, v[62:63], off nt
	global_load_dword v93, v[64:65], off nt
	global_load_dword v94, v[66:67], off nt
	global_load_dword v95, v[68:69], off nt
	global_load_dword v96, v[70:71], off nt
	s_nop 0
	global_load_dword v72, v[72:73], off nt
	v_lshl_add_u64 v[58:59], v[10:11], 0, v[0:1]
	v_or_b32_e32 v0, s5, v37
	v_lshlrev_b32_e32 v0, 12, v0
	v_lshl_add_u64 v[60:61], v[10:11], 0, v[0:1]
	v_or_b32_e32 v0, s5, v38
	v_lshlrev_b32_e32 v0, 12, v0
	v_lshl_add_u64 v[62:63], v[10:11], 0, v[0:1]
	v_or_b32_e32 v0, s5, v39
	v_lshlrev_b32_e32 v0, 12, v0
	v_lshl_add_u64 v[64:65], v[10:11], 0, v[0:1]
	v_or_b32_e32 v0, s5, v40
	v_lshlrev_b32_e32 v0, 12, v0
	v_lshl_add_u64 v[66:67], v[10:11], 0, v[0:1]
	v_or_b32_e32 v0, s5, v41
	v_lshlrev_b32_e32 v0, 12, v0
	v_lshl_add_u64 v[68:69], v[10:11], 0, v[0:1]
	v_or_b32_e32 v0, s5, v42
	v_lshlrev_b32_e32 v0, 12, v0
	v_lshl_add_u64 v[70:71], v[10:11], 0, v[0:1]
	v_or_b32_e32 v0, s5, v43
	v_lshlrev_b32_e32 v0, 12, v0
	v_lshl_add_u64 v[10:11], v[10:11], 0, v[0:1]
	global_load_dword v0, v[58:59], off nt
	s_nop 0
	global_load_dword v58, v[60:61], off nt
	global_load_dword v59, v[62:63], off nt
	s_nop 0
	global_load_dword v60, v[64:65], off nt
	global_load_dword v61, v[66:67], off nt
	global_load_dword v62, v[68:69], off nt
	global_load_dword v63, v[70:71], off nt
	s_nop 0
	global_load_dword v10, v[10:11], off nt
	s_lshl_b32 s0, s5, 1
	s_waitcnt vmcnt(30)
	ds_write2_b32 v49, v74, v75 offset1:66
	s_waitcnt vmcnt(28)
	ds_write2_b32 v49, v76, v77 offset0:132 offset1:198
	s_waitcnt vmcnt(26)
	ds_write2_b32 v52, v78, v79 offset0:8 offset1:74
	s_waitcnt vmcnt(24)
	ds_write2_b32 v50, v80, v81 offset1:66
	s_waitcnt vmcnt(22)
	ds_write2_b32 v50, v85, v86 offset0:132 offset1:198
	s_waitcnt vmcnt(20)
	ds_write2_b32 v53, v87, v88 offset0:8 offset1:74
	s_waitcnt vmcnt(18)
	ds_write2_b32 v51, v89, v90 offset1:66
	s_waitcnt vmcnt(16)
; #define LAS __attribute__((address_space(3)))
; __device__ __forceinline__ unsigned pk2(float lo, float hi) { return f2bf_rne(lo) | (f2bf_rne(hi) << 16); }
; template <bool REMAP>
; __device__ __forceinline__ void p0_transpose_item(const float* W, int K, int N, bf16_t* WT, LAS float* scr, int item, int lane) {
;     ...
;     const int c = lane & 7;
; #pragma unroll
;     for (int j = 0; j < 4; ++j) { const int n = (lane >> 3) + 8 * j; const LAS float* s = scr + (8 * c) * 33 + n;
;         u32x4 o; o.x = pk2(s[0 * 33], s[1 * 33]); o.y = pk2(s[2 * 33], s[3 * 33]); o.z = pk2(s[4 * 33], s[5 * 33]); o.w = pk2(s[6 * 33], s[7 * 33]);
;         *(u32x4*)(WT + (size_t)(r0 + n) * K + k0 + 8 * c) = o; }
;     asm volatile("s_waitcnt lgkmcnt(0)" ::: "memory");
	ds_write2_b32 v51, v91, v92 offset0:132 offset1:198
	s_waitcnt vmcnt(14)
	ds_write2_b32 v54, v82, v83 offset0:8 offset1:74
	s_waitcnt vmcnt(12)
	ds_write2_b32 v54, v84, v93 offset0:140 offset1:206
	s_waitcnt vmcnt(10)
	ds_write2_b32 v55, v94, v95 offset0:16 offset1:82
	s_waitcnt vmcnt(8)
	ds_write2_b32 v55, v96, v72 offset0:148 offset1:214
	s_waitcnt vmcnt(6)
	ds_write2_b32 v56, v0, v58 offset0:24 offset1:90
	s_waitcnt vmcnt(4)
	ds_write2_b32 v56, v59, v60 offset0:156 offset1:222
	s_waitcnt vmcnt(2)
	ds_write2_b32 v57, v61, v62 offset0:32 offset1:98
	s_waitcnt vmcnt(0)
	ds_write2_b32 v57, v63, v10 offset0:164 offset1:230
	s_waitcnt lgkmcnt(0)
	ds_read2_b32 v[10:11], v45 offset1:8
	ds_read2_b32 v[64:65], v45 offset0:33 offset1:41
	ds_read2_b32 v[66:67], v45 offset0:66 offset1:74
	ds_read2_b32 v[68:69], v45 offset0:99 offset1:107
	ds_read2_b32 v[70:71], v45 offset0:132 offset1:140
	s_waitcnt lgkmcnt(4)
	v_bfe_u32 v0, v10, 16, 1
	v_add3_u32 v0, v10, v0, s20
	s_waitcnt lgkmcnt(3)
	v_bfe_u32 v10, v64, 16, 1
	v_lshrrev_b32_e32 v0, 16, v0
	v_add3_u32 v10, v64, v10, s20
	ds_read2_b32 v[72:73], v45 offset0:165 offset1:173
	v_and_or_b32 v58, v10, s21, v0
	s_waitcnt lgkmcnt(3)
	v_bfe_u32 v0, v66, 16, 1
	v_add3_u32 v0, v66, v0, s20
	s_waitcnt lgkmcnt(2)
	v_bfe_u32 v10, v68, 16, 1
	ds_read2_b32 v[74:75], v45 offset0:198 offset1:206
	v_lshrrev_b32_e32 v0, 16, v0
	v_add3_u32 v10, v68, v10, s20
	ds_read2_b32 v[76:77], v45 offset0:231 offset1:239
	v_and_or_b32 v59, v10, s21, v0
	s_waitcnt lgkmcnt(3)
	v_bfe_u32 v0, v70, 16, 1
	v_add3_u32 v0, v70, v0, s20
	s_waitcnt lgkmcnt(2)
	v_bfe_u32 v10, v72, 16, 1
	v_lshrrev_b32_e32 v0, 16, v0
	v_add3_u32 v10, v72, v10, s20
	v_and_or_b32 v60, v10, s21, v0
	s_waitcnt lgkmcnt(1)
	v_bfe_u32 v0, v74, 16, 1
	v_add3_u32 v0, v74, v0, s20
	s_waitcnt lgkmcnt(0)
	v_bfe_u32 v10, v76, 16, 1
	v_lshrrev_b32_e32 v0, 16, v0
	v_add3_u32 v10, v76, v10, s20
	v_and_or_b32 v61, v10, s21, v0
	v_or_b32_e32 v0, s4, v44
	v_lshl_add_u64 v[62:63], v[4:5], 0, s[0:1]
	v_lshlrev_b32_e32 v0, 11, v0
	v_lshl_add_u64 v[78:79], v[62:63], 0, v[0:1]
	v_bfe_u32 v0, v11, 16, 1
	v_add3_u32 v0, v11, v0, s20
	v_bfe_u32 v10, v65, 16, 1
	v_lshrrev_b32_e32 v0, 16, v0
	v_add3_u32 v10, v65, v10, s20
	global_store_dwordx4 v[78:79], v[58:61], off sc1
	s_nop 1
	v_and_or_b32 v58, v10, s21, v0
	v_bfe_u32 v0, v67, 16, 1
	v_add3_u32 v0, v67, v0, s20
	v_bfe_u32 v10, v69, 16, 1
	v_lshrrev_b32_e32 v0, 16, v0
	v_add3_u32 v10, v69, v10, s20
	v_and_or_b32 v59, v10, s21, v0
	v_bfe_u32 v0, v71, 16, 1
	v_add3_u32 v0, v71, v0, s20
	v_bfe_u32 v10, v73, 16, 1
	v_lshrrev_b32_e32 v0, 16, v0
	v_add3_u32 v10, v73, v10, s20
	v_and_or_b32 v60, v10, s21, v0
	v_bfe_u32 v0, v75, 16, 1
	v_add3_u32 v0, v75, v0, s20
	v_bfe_u32 v10, v77, 16, 1
	v_lshrrev_b32_e32 v0, 16, v0
	v_add3_u32 v10, v77, v10, s20
	v_and_or_b32 v61, v10, s21, v0
	v_or_b32_e32 v0, s4, v46
	v_lshlrev_b32_e32 v0, 11, v0
	ds_read2_b32 v[10:11], v45 offset0:16 offset1:24
	v_lshl_add_u64 v[64:65], v[62:63], 0, v[0:1]
	global_store_dwordx4 v[64:65], v[58:61], off sc1
	ds_read2_b32 v[64:65], v45 offset0:49 offset1:57
	ds_read2_b32 v[66:67], v45 offset0:82 offset1:90
	ds_read2_b32 v[68:69], v45 offset0:115 offset1:123
	s_waitcnt lgkmcnt(3)
	v_bfe_u32 v0, v10, 16, 1
	v_add3_u32 v0, v10, v0, s20
	s_waitcnt lgkmcnt(2)
	v_bfe_u32 v10, v64, 16, 1
	ds_read2_b32 v[70:71], v45 offset0:148 offset1:156
	v_lshrrev_b32_e32 v0, 16, v0
	v_add3_u32 v10, v64, v10, s20
	ds_read2_b32 v[72:73], v45 offset0:181 offset1:189
	v_and_or_b32 v58, v10, s21, v0
	s_waitcnt lgkmcnt(3)
	v_bfe_u32 v0, v66, 16, 1
	v_add3_u32 v0, v66, v0, s20
	s_waitcnt lgkmcnt(2)
	v_bfe_u32 v10, v68, 16, 1
	ds_read2_b32 v[74:75], v45 offset0:214 offset1:222
	v_lshrrev_b32_e32 v0, 16, v0
	v_add3_u32 v10, v68, v10, s20
	ds_read2_b32 v[76:77], v45 offset0:247 offset1:255
	v_and_or_b32 v59, v10, s21, v0
	s_waitcnt lgkmcnt(3)
	v_bfe_u32 v0, v70, 16, 1
	v_add3_u32 v0, v70, v0, s20
	s_waitcnt lgkmcnt(2)
	v_bfe_u32 v10, v72, 16, 1
	v_lshrrev_b32_e32 v0, 16, v0
	v_add3_u32 v10, v72, v10, s20
	v_and_or_b32 v60, v10, s21, v0
	s_waitcnt lgkmcnt(1)
	v_bfe_u32 v0, v74, 16, 1
	v_add3_u32 v0, v74, v0, s20
	s_waitcnt lgkmcnt(0)
	v_bfe_u32 v10, v76, 16, 1
	v_lshrrev_b32_e32 v0, 16, v0
	v_add3_u32 v10, v76, v10, s20
	v_and_or_b32 v61, v10, s21, v0
	v_or_b32_e32 v0, s4, v47
	v_lshlrev_b32_e32 v0, 11, v0
	v_lshl_add_u64 v[78:79], v[62:63], 0, v[0:1]
	v_bfe_u32 v0, v11, 16, 1
	v_add3_u32 v0, v11, v0, s20
	v_bfe_u32 v10, v65, 16, 1
	v_lshrrev_b32_e32 v0, 16, v0
	v_add3_u32 v10, v65, v10, s20
	global_store_dwordx4 v[78:79], v[58:61], off sc1
	s_nop 1
	v_and_or_b32 v58, v10, s21, v0
	v_bfe_u32 v0, v67, 16, 1
	v_add3_u32 v0, v67, v0, s20
	v_bfe_u32 v10, v69, 16, 1
	v_lshrrev_b32_e32 v0, 16, v0
	v_add3_u32 v10, v69, v10, s20
	v_and_or_b32 v59, v10, s21, v0
	v_bfe_u32 v0, v71, 16, 1
	v_add3_u32 v0, v71, v0, s20
	v_bfe_u32 v10, v73, 16, 1
	v_lshrrev_b32_e32 v0, 16, v0
	v_add3_u32 v10, v73, v10, s20
	v_and_or_b32 v60, v10, s21, v0
	v_bfe_u32 v0, v75, 16, 1
	v_add3_u32 v0, v75, v0, s20
	v_bfe_u32 v10, v77, 16, 1
	v_lshrrev_b32_e32 v0, 16, v0
	v_add3_u32 v10, v77, v10, s20
	v_and_or_b32 v61, v10, s21, v0
	v_or_b32_e32 v0, s4, v48
	v_lshlrev_b32_e32 v0, 11, v0
	v_lshl_add_u64 v[10:11], v[62:63], 0, v[0:1]
	global_store_dwordx4 v[10:11], v[58:61], off sc1
	s_waitcnt lgkmcnt(0)
	s_mov_b64 s[4:5], 0

; __device__ __forceinline__ void p0_mod_item(const Args& a, LAS unsigned char* lds, int it, int tid, int lane, int wave) {
;     ...
;     float* mod = (float*)(a.ws + WS_MOD);
;     const float* bm = a.in[8] + (size_t)l * 3072;
;     for (int e = tid; e < NMOD * 32; e += 512) { const int row = e >> 5, c = e & 31; mod[((size_t)l * NMOD + row) * 3072 + col0 + c] = red[e] + bm[col0 + c]; }
.LBB0_122:
	global_load_dword v10, v[0:1], off
	v_ashrrev_i32_e32 v6, 5, v5
	ds_read_b32 v11, v4
	v_ashrrev_i32_e32 v7, 31, v6
	v_add_u32_e32 v8, 0x200, v5
	v_lshl_add_u64 v[6:7], s[20:21], 0, v[6:7]
	v_cmp_lt_i32_e32 vcc, s41, v5
	v_mov_b32_e32 v5, v8
	v_mad_u64_u32 v[8:9], s[46:47], v6, s22, v[2:3]
	v_mov_b32_e32 v6, v9
	v_mad_u64_u32 v[6:7], s[46:47], v7, s22, v[6:7]
	v_add_u32_e32 v4, 0x800, v4
	s_or_b64 s[18:19], vcc, s[18:19]
	v_mov_b32_e32 v9, v6
	s_waitcnt vmcnt(0) lgkmcnt(0)
	v_add_f32_e32 v6, v11, v10
	global_store_dword v[8:9], v6, off sc1
	s_andn2_b64 exec, exec, s[18:19]
	s_cbranch_execnz .LBB0_122
	s_branch .LBB0_73

; __device__ __forceinline__ unsigned xb_add(unsigned* p, unsigned v) { return __hip_atomic_fetch_add(p, v, __ATOMIC_RELAXED, __HIP_MEMORY_SCOPE_AGENT); }
; __device__ __forceinline__ void xcd_barrier(const XcdBarrier& b) {
;     ...
;         const unsigned old = xb_add(&bar[XB_XSUB(b.x)], 1u);
;         const unsigned gen = old / nloc;
;         if (old + 1u == (gen + 1u) * nloc) {
;             __builtin_amdgcn_fence(__ATOMIC_RELEASE, "agent");
;             asm volatile("s_waitcnt vmcnt(0)" ::: "memory");
;             const unsigned og = xb_add(&bar[XB_TOP], 1u);
;             const unsigned tg = og / nx;
;             if (og + 1u == (tg + 1u) * nx) xb_add(&bar[XB_TOPGEN], 1u);
.LBB0_151:
	s_waitcnt lgkmcnt(0)
	v_readfirstlane_b32 s14, v2
	v_readfirstlane_b32 s15, v0
	s_lshl_b32 s4, s3, 8
	s_add_u32 s6, s78, 0x1701400
	s_addc_u32 s7, s79, 0
	s_add_u32 s6, s6, s4
	s_addc_u32 s7, s7, 0
	s_add_u32 s8, s6, 0x1000
	s_addc_u32 s9, s7, 0
	s_add_u32 s10, s78, 0x1703400
	s_addc_u32 s11, s79, 0
	v_mov_b32_e32 v0, 0
	v_mov_b32_e32 v1, 1
	global_atomic_add v2, v0, v1, s[6:7] sc0
	buffer_inv sc1
	s_waitcnt vmcnt(1)
	v_readfirstlane_b32 s4, v2
	s_nop 3
	s_add_i32 s4, s4, 1
	s_cmp_lg_u32 s4, s14
	s_cbranch_scc1 .Lxb_local_p
	global_atomic_add v0, v1, s[10:11]
	s_mov_b32 s4, 0
